# static placement variant: RWKV chains paired with GLA chains, HGRN/RetNet chains alone on their CU
# speedup vs baseline: 1.0443x; 1.0189x over previous
.LBB0_285:
	s_or_b64 exec, exec, s[0:1]
	v_readlane_b32 s4, v254, 3
	v_readlane_b32 s18, v254, 17
	v_readlane_b32 s19, v254, 18
	s_add_u32 s0, s18, 0x5790000
	v_readlane_b32 s5, v254, 4
	v_readlane_b32 s6, v254, 5
	v_readlane_b32 s7, v254, 6
	v_readlane_b32 s8, v254, 7
	v_readlane_b32 s9, v254, 8
	v_readlane_b32 s10, v254, 9
	v_readlane_b32 s11, v254, 10
	v_readlane_b32 s12, v254, 11
	v_readlane_b32 s13, v254, 12
	v_readlane_b32 s14, v254, 13
	v_readlane_b32 s15, v254, 14
	v_readlane_b32 s16, v254, 15
	v_readlane_b32 s17, v254, 16
	v_writelane_b32 v254, s0, 62
	s_addc_u32 s0, s19, 0
	s_add_u32 s26, s74, 0x1000
	s_addc_u32 s27, s75, 0
	v_writelane_b32 v254, s0, 63
	s_add_u32 s0, s74, 0x1200
	s_addc_u32 s1, s75, 0
	s_mov_b32 s87, 0
	v_writelane_b32 v255, s0, 0
	v_mov_b32_e32 v28, 0
	s_movk_i32 s7, 0x1e20
	v_writelane_b32 v255, s1, 1
	s_add_u32 s0, s74, 0x1400
	s_addc_u32 s1, s75, 0
	v_writelane_b32 v255, s0, 2
	s_movk_i32 s24, 0x1000
	s_mov_b32 s90, 0xbfb8aa3b
	v_writelane_b32 v255, s1, 3
	s_add_u32 s0, s74, 0x1600
	s_addc_u32 s1, s75, 0
	v_writelane_b32 v255, s0, 4
	s_mov_b32 s91, 0x800000
	s_mov_b32 s92, 0x3f317217
	v_writelane_b32 v255, s1, 5
	s_add_u32 s0, s74, 0x1800
	s_addc_u32 s1, s75, 0
	v_writelane_b32 v255, s0, 6
	s_mov_b32 s93, 0x7f800000
	s_mov_b32 s6, 0x3e3504f3
	v_writelane_b32 v255, s1, 7
	s_add_u32 s0, s74, 0x1a00
	s_addc_u32 s1, s75, 0
	v_writelane_b32 v255, s0, 8
	s_movk_i32 s94, 0x800
	v_mov_b32_e32 v71, 0x42800000
	v_writelane_b32 v255, s1, 9
	s_add_u32 s0, s74, 0x1c00
	s_addc_u32 s1, s75, 0
	v_writelane_b32 v255, s0, 10
	v_mov_b32_e32 v72, 0x1800
	v_mov_b32_e32 v73, 0x1600
	v_writelane_b32 v255, s1, 11
	s_add_u32 s0, s74, 0x1e00
	s_addc_u32 s1, s75, 0
	v_writelane_b32 v255, s0, 12
	v_mov_b32_e32 v74, 0x3e000000
	v_mov_b32_e32 v75, 0x41b17218
	v_writelane_b32 v255, s1, 13
	s_add_u32 s0, s18, 0x4790000
	v_writelane_b32 v255, s0, 14
	s_addc_u32 s0, s19, 0
	v_writelane_b32 v255, s0, 15
	s_add_u32 s0, s18, 0x7090000
	v_writelane_b32 v255, s0, 16
	s_addc_u32 s0, s19, 0
	v_writelane_b32 v255, s0, 17
	s_add_u32 s0, s18, 0x5f90000
	v_writelane_b32 v255, s0, 18
	s_addc_u32 s0, s19, 0
	s_add_u32 s31, s18, 0x4690000
	v_writelane_b32 v255, s0, 19
	s_addc_u32 s0, s19, 0
	v_writelane_b32 v255, s0, 20
	s_add_u32 s0, s18, 0x4500000
	v_writelane_b32 v255, s0, 22
	s_addc_u32 s0, s19, 0
	v_writelane_b32 v255, s0, 24
	s_add_u32 s0, s18, 0x4400000
	v_writelane_b32 v255, s0, 26
	s_addc_u32 s0, s19, 0
	v_writelane_b32 v255, s0, 42
	s_add_i32 s3, 0, 0x10010
	s_add_i32 s0, 0, 0x3000
	v_writelane_b32 v255, s0, 44
	v_mov_b32_e32 v70, s3
	v_mov_b32_e32 v76, 0xc00
	v_mov_b32_e32 v77, 0xb00
	v_mov_b32_e32 v78, 0x1000
	s_waitcnt lgkmcnt(0)
	s_barrier
	s_mov_b32 s99, -1
	s_mov_b32 s100, 0
	s_cmp_lg_u32 s28, 0x200
	s_cbranch_scc1 .Lmap_done_0
	s_movk_i32 s100, 0x140
	s_cmp_ge_u32 s2, 320
	s_cbranch_scc1 .Lmap_done_0
	s_mov_b32 s99, s2
	s_cmp_lt_u32 s2, 192
	s_cbranch_scc1 .Lmap_done_0
	s_add_u32 s99, s2, 64
	s_cmp_lt_u32 s2, 256
	s_cbranch_scc1 .Lmap_done_0
	s_sub_u32 s99, s2, 64

.LBB0_1268:
	s_or_b64 exec, exec, s[0:1]
	v_readlane_b32 s52, v255, 26
	v_readlane_b32 s58, v255, 32
	v_readlane_b32 s59, v255, 33
	s_add_u32 s92, s58, 0x2000
	s_addc_u32 s93, s59, 0
	s_add_u32 s0, s58, 0x3000
	s_addc_u32 s1, s59, 0
	v_writelane_b32 v254, s0, 37
	v_readlane_b32 s53, v255, 27
	v_readlane_b32 s54, v255, 28
	v_writelane_b32 v254, s1, 38
	s_add_u32 s0, s58, 0x2200
	s_addc_u32 s1, s59, 0
	v_writelane_b32 v254, s0, 58
	v_readlane_b32 s55, v255, 29
	v_readlane_b32 s56, v255, 30
	v_writelane_b32 v254, s1, 59
	s_add_u32 s0, s58, 0x3200
	s_addc_u32 s1, s59, 0
	v_readlane_b32 s57, v255, 31
	v_readlane_b32 s60, v255, 34
	v_readlane_b32 s61, v255, 35
	v_readlane_b32 s62, v255, 36
	v_readlane_b32 s63, v255, 37
	v_readlane_b32 s64, v255, 38
	v_readlane_b32 s65, v255, 39
	v_readlane_b32 s66, v255, 40
	v_readlane_b32 s67, v255, 41
	v_writelane_b32 v255, s0, 20
	s_mov_b32 s11, 0
	v_mov_b32_e32 v28, 0
	v_writelane_b32 v255, s1, 21
	s_add_u32 s0, s58, 0x2400
	s_addc_u32 s1, s59, 0
	v_writelane_b32 v255, s0, 22
	s_movk_i32 s3, 0x1e20
	s_movk_i32 s94, 0x1000
	v_writelane_b32 v255, s1, 23
	s_add_u32 s0, s58, 0x3400
	s_addc_u32 s1, s59, 0
	v_writelane_b32 v255, s0, 24
	s_mov_b32 s95, 0xbfb8aa3b
	s_mov_b32 s52, 0x800000
	v_writelane_b32 v255, s1, 25
	s_add_u32 s0, s58, 0x2600
	s_addc_u32 s1, s59, 0
	v_writelane_b32 v254, s0, 60
	s_mov_b32 s53, 0x3f317217
	s_mov_b32 s54, 0x7f800000
	v_writelane_b32 v254, s1, 61
	s_add_u32 s0, s58, 0x3600
	s_addc_u32 s1, s59, 0
	v_writelane_b32 v255, s0, 0
	s_mov_b32 s4, 0x3e3504f3
	s_movk_i32 s55, 0x800
	v_writelane_b32 v255, s1, 1
	s_add_u32 s0, s58, 0x2800
	s_addc_u32 s1, s59, 0
	v_writelane_b32 v255, s0, 2
	v_mov_b32_e32 v73, 0x42800000
	v_mov_b32_e32 v74, 0x1800
	v_writelane_b32 v255, s1, 3
	s_add_u32 s0, s58, 0x3800
	s_addc_u32 s1, s59, 0
	v_writelane_b32 v255, s0, 4
	v_mov_b32_e32 v75, 0x1600
	v_mov_b32_e32 v76, 0x3e000000
	v_writelane_b32 v255, s1, 5
	s_add_u32 s0, s58, 0x2a00
	s_addc_u32 s1, s59, 0
	v_writelane_b32 v255, s0, 6
	v_mov_b32_e32 v77, 0x41b17218
	v_mov_b32_e32 v78, 0xc00
	v_writelane_b32 v255, s1, 7
	s_add_u32 s0, s58, 0x3a00
	s_addc_u32 s1, s59, 0
	v_writelane_b32 v255, s0, 8
	v_mov_b32_e32 v79, 0xb00
	v_mov_b32_e32 v80, 0x1000
	v_writelane_b32 v255, s1, 9
	s_add_u32 s0, s58, 0x2c00
	s_addc_u32 s1, s59, 0
	v_writelane_b32 v255, s0, 10
	s_waitcnt lgkmcnt(0)
	s_barrier
	v_writelane_b32 v255, s1, 11
	s_add_u32 s0, s58, 0x3c00
	s_addc_u32 s1, s59, 0
	s_add_u32 s96, s58, 0x2e00
	s_addc_u32 s97, s59, 0
	s_add_u32 s90, s58, 0x3e00
	v_writelane_b32 v255, s0, 12
	s_addc_u32 s91, s59, 0
	s_add_i32 s5, 0, 0x10010
	v_writelane_b32 v255, s1, 13
	v_mov_b32_e32 v72, s5
	s_mov_b32 s99, -1
	s_mov_b32 s100, 0
	s_cmp_lg_u32 s28, 0x200
	s_cbranch_scc1 .Lmap_done_1
	s_movk_i32 s100, 0x140
	s_cmp_ge_u32 s2, 320
	s_cbranch_scc1 .Lmap_done_1
	s_mov_b32 s99, s2
	s_cmp_lt_u32 s2, 192
	s_cbranch_scc1 .Lmap_done_1
	s_add_u32 s99, s2, 64
	s_cmp_lt_u32 s2, 256
	s_cbranch_scc1 .Lmap_done_1
	s_sub_u32 s99, s2, 64
